# ssdc: per-item dt and a_log loads issued at item start instead of after the tile staging (one dependent round trip less)
# baseline (speedup 1.0000x reference)
; __device__ __forceinline__ void ph_ssdc(LAS unsigned char* lds) {
;     ...
;             if (wid < 4) {
;                 const float A = -__expf(a_log[g * 4 + wid]);
;                 const float d0 = DT[(unsigned)((trow0 + 2 * lane) * 32 + g * 4 + wid)], d1 = DT[(unsigned)((trow0 + 2 * lane + 1) * 32 + g * 4 + wid)];
.LBB0_957:
	s_cmp_gt_i32 s7, 3
	s_cbranch_scc1 .Lssdc_nodt
	s_and_b32 s20, s42, 7
	s_lshl_b32 s21, s20, 2
	s_add_i32 s4, s21, s7
	s_ashr_i32 s5, s4, 31
	s_lshl_b64 s[4:5], s[4:5], 2
	s_waitcnt lgkmcnt(0)
	s_add_u32 s4, s84, s4
	s_addc_u32 s5, s85, s5
	global_load_dword v133, v1, s[4:5]
	s_lshl_b32 s4, s42, 4
	s_and_b32 s4, s4, 0xffffff80
	v_and_b32_e32 v0, 63, v221
	v_lshlrev_b32_e32 v0, 1, v0
	v_or_b32_e32 v0, s4, v0
	v_lshl_or_b32 v0, v0, 5, s21
	v_add_u32_e32 v0, s7, v0
	v_lshl_add_u64 v[2:3], v[0:1], 2, s[80:81]
	v_add_u32_e32 v0, 32, v0
	v_lshl_add_u64 v[4:5], v[0:1], 2, s[80:81]
	global_load_dword v142, v[2:3], off
	global_load_dword v143, v[4:5], off

; __device__ __forceinline__ void ph_ssdc(LAS unsigned char* lds) {
;     ...
;             if (wid < 4) {
;                 const float A = -__expf(a_log[g * 4 + wid]);
;                 const float d0 = DT[(unsigned)((trow0 + 2 * lane) * 32 + g * 4 + wid)], d1 = DT[(unsigned)((trow0 + 2 * lane + 1) * 32 + g * 4 + wid)];
;                 const float x0 = d0 * A, x1 = x0 + d1 * A;
;                 float incl = x1;
; #pragma unroll
;                 for (int o = 1; o < 64; o <<= 1) { const float t = __shfl_up(incl, o); if (lane >= o) incl += t; }
;                 const float excl = incl - x1;
;                 acs[wid * 128 + 2 * lane] = excl + x0; acs[wid * 128 + 2 * lane + 1] = excl + x1;
;                 dts[wid * 128 + 2 * lane] = d0; dts[wid * 128 + 2 * lane + 1] = d1;
;             }
.LBB0_959:
	s_lshl_b32 s2, s42, 4
	s_andn2_b64 vcc, exec, s[4:5]
	s_and_b32 s18, s2, 0xffffff80
	s_cbranch_vccnz .LBB0_961
	s_lshl_b32 s21, s19, 2
	s_add_i32 s4, s21, s7
	s_ashr_i32 s5, s4, 31
	s_lshl_b64 s[4:5], s[4:5], 2
	s_waitcnt lgkmcnt(0)
	s_add_u32 s4, s84, s4
	v_and_b32_e32 v8, 63, v8
	s_addc_u32 s5, s85, s5
	v_mov_b32_e32 v6, v133
	v_lshlrev_b32_e32 v9, 1, v8
	v_or_b32_e32 v0, s18, v9
	v_lshl_or_b32 v0, v0, 5, s21
	v_add_u32_e32 v0, s7, v0
	v_lshl_add_u64 v[2:3], v[0:1], 2, s[80:81]
	v_add_u32_e32 v0, 32, v0
	v_lshl_add_u64 v[4:5], v[0:1], 2, s[80:81]
	v_mov_b32_e32 v2, v142
	s_nop 0
	v_mov_b32_e32 v3, v143
	v_add_u32_e32 v4, -1, v236
	v_cmp_lt_i32_e32 vcc, v4, v243
	v_or_b32_e32 v9, s14, v9
	v_lshl_add_u32 v9, v9, 2, 0
	v_cndmask_b32_e32 v4, v4, v236, vcc
	v_lshlrev_b32_e32 v10, 2, v4
	s_waitcnt vmcnt(2)
	v_mul_f32_e32 v0, 0x3fb8aa3b, v6
	v_exp_f32_e32 v0, v0
	s_waitcnt vmcnt(0)
	v_pk_mul_f32 v[4:5], v[2:3], v[0:1] op_sel_hi:[1,0] neg_lo:[0,1]
	s_nop 0
	v_pk_fma_f32 v[6:7], v[2:3], v[0:1], v[4:5] op_sel:[0,0,1] op_sel_hi:[1,0,0] neg_lo:[0,1,1] neg_hi:[0,0,1]
	ds_bpermute_b32 v0, v10, v6
	v_add_u32_e32 v5, -2, v236
	v_cmp_lt_i32_e32 vcc, v5, v243
	v_add_u32_e32 v10, -4, v236
	s_waitcnt lgkmcnt(0)
	v_add_f32_e32 v0, v6, v0
	v_cndmask_b32_e32 v5, v5, v236, vcc
	v_cmp_eq_u32_e32 vcc, 0, v8
	v_lshlrev_b32_e32 v5, 2, v5
	s_nop 0
	v_cndmask_b32_e32 v0, v0, v6, vcc
	ds_bpermute_b32 v5, v5, v0
	v_cmp_lt_i32_e32 vcc, v10, v243
	s_waitcnt lgkmcnt(0)
	v_add_f32_e32 v5, v0, v5
	v_cndmask_b32_e32 v10, v10, v236, vcc
	v_cmp_gt_u32_e32 vcc, 2, v8
	v_lshlrev_b32_e32 v10, 2, v10
	s_nop 0
	v_cndmask_b32_e32 v0, v5, v0, vcc
	ds_bpermute_b32 v5, v10, v0
	v_add_u32_e32 v10, -8, v236
	v_cmp_lt_i32_e32 vcc, v10, v243
	s_waitcnt lgkmcnt(0)
	v_add_f32_e32 v5, v0, v5
	v_cndmask_b32_e32 v10, v10, v236, vcc
	v_cmp_gt_u32_e32 vcc, 4, v8
	v_lshlrev_b32_e32 v10, 2, v10
	s_nop 0
	v_cndmask_b32_e32 v0, v5, v0, vcc
	ds_bpermute_b32 v5, v10, v0
	v_add_u32_e32 v10, -16, v236
	v_cmp_lt_i32_e32 vcc, v10, v243
	s_waitcnt lgkmcnt(0)
	v_add_f32_e32 v5, v0, v5
	v_cndmask_b32_e32 v10, v10, v236, vcc
	v_cmp_gt_u32_e32 vcc, 8, v8
	v_lshlrev_b32_e32 v10, 2, v10
	s_nop 0
	v_cndmask_b32_e32 v0, v5, v0, vcc
	ds_bpermute_b32 v5, v10, v0
	v_subrev_u32_e32 v10, 32, v236
	v_cmp_lt_i32_e32 vcc, v10, v243
	s_waitcnt lgkmcnt(0)
	v_add_f32_e32 v5, v0, v5
	v_cndmask_b32_e32 v10, v10, v236, vcc
	v_cmp_gt_u32_e32 vcc, 16, v8
	v_lshlrev_b32_e32 v10, 2, v10
	s_nop 0
	v_cndmask_b32_e32 v0, v5, v0, vcc
	ds_bpermute_b32 v5, v10, v0
	v_cmp_gt_u32_e32 vcc, 32, v8
	v_add_u32_e32 v10, 0x20800, v9
	v_add_u32_e32 v9, 0x20000, v9
	s_waitcnt lgkmcnt(0)
	v_add_f32_e32 v5, v0, v5
	v_cndmask_b32_e32 v0, v5, v0, vcc
	v_sub_f32_e32 v5, v0, v6
	v_pk_mov_b32 v[6:7], v[4:5], v[6:7] op_sel:[1,0]
	s_nop 0
	v_pk_add_f32 v[4:5], v[4:5], v[6:7]
	ds_write_b64 v10, v[4:5]
	ds_write_b64 v9, v[2:3]
